# context-attention tasks moved from ph3 (second task on blocks 0..63) to the slack of ph4 on blocks 448..511
# speedup vs baseline: 1.0118x; 1.0011x over previous
; #define KARGP(z_) ((const P*)(const void*)((const __attribute__((address_space(4))) char*)__builtin_amdgcn_kernarg_segment_ptr() + (z_)))
; __device__ __forceinline__ void ph_attn(const P& p, int need_ctx, char* smem) {
;     ...
;   int ntask = 8 * 4 * 16 + (need_ctx ? 8 * 4 * 2 : 0);
;   for (int task = (blockIdx.x + zz); task < ntask; task += (gridDim.x + zz)) {
;     int b, h, qrow0, nkt;
;     if (task < 512) { b = task >> 6; h = (task >> 4) & 3; int qt = task & 15; qrow0 = b * 2048 + qt * 128; nkt = 36; }
;     else { int t2 = task - 512; b = t2 >> 3; h = (t2 >> 1) & 3; int qt = t2 & 1; qrow0 = T_LAT + b * 256 + qt * 128; nkt = 4; }
; __global__ void __launch_bounds__(NTHR, 2) mega(P p) {
;     ...
;       case 4: {
;         OPAQUE_Z; const P& q = *KARGP(zz);
;         ph_scan3(q, l, need_ctx, smem);
;         break;
.LBB0_1222:
	v_readlane_b32 s88, v254, 18
	v_readlane_b32 s40, v254, 34
	v_readlane_b32 s87, v254, 17
	v_readlane_b32 s89, v254, 19
	v_readlane_b32 s90, v254, 20
	s_movk_i32 s54, 0x100
	v_readlane_b32 s94, v254, 40
	v_readlane_b32 s41, v254, 35
	s_nop 0
	s_and_b64 vcc, exec, s[40:41]
	s_cbranch_vccnz .LBB0_1223
	s_cmp_lt_u32 s87, 0x1c0
	s_cbranch_scc1 .LBB0_1223
	s_load_dwordx2 s[2:3], s[88:89], 0x118
	s_mov_b32 s20, 0
	s_movk_i32 s16, 0x240
	s_add_i32 s17, s87, 64
	v_mov_b32_e32 v196, 0x80
	s_branch .Lattn_entry

; __device__ __forceinline__ void ph_attn(const P& p, int need_ctx, char* smem) {
;     ...
;   int ntask = 8 * 4 * 16 + (need_ctx ? 8 * 4 * 2 : 0);
;   for (int task = (blockIdx.x + zz); task < ntask; task += (gridDim.x + zz)) {
.LBB0_1239:
	s_or_b64 exec, exec, s[6:7]
	s_and_b64 s[0:1], s[40:41], exec
	s_movk_i32 s0, 0x200
	s_mov_b32 s20, 0
	s_cselect_b32 s16, 0x200, s0
	s_add_i32 s17, s20, s87
	v_mov_b32_e32 v196, 0x80
	s_cmp_ge_i32 s17, s16
	s_cbranch_scc1 .LBB0_1262
